# Resid epilogues: f32 results staged through idle LDS buffers per (ai,bj) quarter tile, whole-row coalesced dwordx4 stores
# speedup vs baseline: 1.0168x; 1.0168x over previous
.LBB0_799:
	v_add_u32_e32 v151, s27, v133
	v_add_u32_e32 v140, s26, v149
	s_mov_b32 s26, 0x8000
	v_add_u32_e32 v142, 0xffff8000, v151
	v_ashrrev_i32_e32 v143, 31, v151
	v_cmp_gt_i32_e32 vcc, s26, v151
	v_readlane_b32 s64, v254, 27
	v_ashrrev_i32_e32 v141, 31, v140
	v_cndmask_b32_e32 v143, 0, v143, vcc
	v_cndmask_b32_e32 v142, v142, v151, vcc
	v_lshlrev_b64 v[144:145], 12, v[142:143]
	v_min_i32_e32 v142, 0x8000, v151
	v_ashrrev_i32_e32 v142, 12, v142
	v_mul_i32_i24_e32 v142, 0x2400, v142
	v_ashrrev_i32_e32 v143, 31, v142
	v_readlane_b32 s65, v254, 28
	v_lshlrev_b64 v[140:141], 2, v[140:141]
	v_mov_b32_e32 v152, s9
	v_lshl_add_u64 v[142:143], v[142:143], 2, s[64:65]
	v_mov_b32_e32 v153, s11
	v_mov_b32_e32 v154, s8
	v_mov_b32_e32 v155, s10
	v_lshl_add_u64 v[168:169], v[142:143], 0, v[140:141]
	s_movk_i32 s27, 0x2000
	v_cndmask_b32_e32 v147, v152, v153, vcc
	v_cndmask_b32_e32 v146, v154, v155, vcc
	v_add_co_u32_e64 v142, s[6:7], s27, v168
	v_lshl_add_u64 v[146:147], v[146:147], 0, v[144:145]
	s_nop 0
	v_addc_co_u32_e64 v143, s[6:7], 0, v169, s[6:7]
	v_lshl_add_u64 v[142:143], v[146:147], 0, v[140:141]
	v_readlane_b32 s48, v251, 19
	v_readlane_b32 s52, v251, 23
	v_readlane_b32 s53, v251, 24
	v_readlane_b32 s54, v251, 25
	v_readlane_b32 s55, v251, 26
	v_readlane_b32 s56, v251, 27
	v_readlane_b32 s57, v251, 28
	v_readlane_b32 s58, v251, 29
	v_readlane_b32 s59, v251, 30
	v_readlane_b32 s60, v251, 31
	v_readlane_b32 s61, v251, 32
	v_readlane_b32 s62, v251, 33
	v_readlane_b32 s63, v251, 34
	s_mov_b64 s[52:53], s[56:57]
	s_mov_b64 s[54:55], s[58:59]
	v_mov_b32_e32 v156, s55
	v_mov_b32_e32 v157, s53
	v_mov_b32_e32 v158, s54
	v_mov_b32_e32 v159, s52
	v_cndmask_b32_e32 v147, v156, v157, vcc
	v_cndmask_b32_e32 v146, v158, v159, vcc
	v_lshl_add_u64 v[144:145], v[146:147], 0, v[144:145]
	v_lshl_add_u64 v[144:145], v[144:145], 0, v[140:141]
	s_mov_b64 s[38:39], 0x2000
	v_lshl_add_u64 v[146:147], v[168:169], 0, s[38:39]
	s_movk_i32 s30, 0x7ff0
	v_cmp_gt_i32_e32 vcc, s30, v151
	s_movk_i32 s31, 0x7fe0
	s_movk_i32 s34, 0x7fd0
	v_readlane_b32 s49, v251, 20
	v_readlane_b32 s50, v251, 21
	v_readlane_b32 s51, v251, 22
	s_mov_b64 s[56:57], s[60:61]
	s_mov_b64 s[58:59], s[62:63]
	v_readlane_b32 s48, v251, 3
	v_readlane_b32 s49, v251, 4
	v_readlane_b32 s50, v251, 5
	v_readlane_b32 s51, v251, 6
	v_readlane_b32 s52, v251, 7
	v_readlane_b32 s53, v251, 8
	v_readlane_b32 s54, v251, 9
	v_readlane_b32 s55, v251, 10
	v_readlane_b32 s56, v251, 11
	v_readlane_b32 s57, v251, 12
	v_readlane_b32 s58, v251, 13
	v_readlane_b32 s59, v251, 14
	v_readlane_b32 s60, v251, 15
	v_readlane_b32 s61, v251, 16
	v_readlane_b32 s62, v251, 17
	v_readlane_b32 s63, v251, 18
	v_readlane_b32 s48, v252, 4
	v_readlane_b32 s49, v252, 5
	v_readlane_b32 s50, v252, 6
	v_readlane_b32 s51, v252, 7
	v_readlane_b32 s52, v252, 8
	v_readlane_b32 s53, v252, 9
	v_readlane_b32 s54, v252, 10
	v_readlane_b32 s55, v252, 11
	v_readlane_b32 s56, v252, 12
	v_readlane_b32 s57, v252, 13
	v_readlane_b32 s58, v252, 14
	v_readlane_b32 s59, v252, 15
	v_readlane_b32 s60, v252, 16
	v_readlane_b32 s61, v252, 17
	v_readlane_b32 s62, v252, 18
	v_readlane_b32 s63, v252, 19
	s_mov_b64 s[94:95], 0x10000
	s_mov_b64 s[96:97], 0x50000
	global_load_dwordx4 v[152:155], v[146:147], off
	global_load_dwordx4 v[156:159], v[146:147], off offset:64
	global_load_dwordx4 v[160:163], v[146:147], off offset:512
	global_load_dwordx4 v[164:167], v[146:147], off offset:576
	v_mov_b64_e32 v[248:249], v[142:143]
	v_mov_b64_e32 v[140:141], v[144:145]
	global_load_dwordx4 v[168:171], v[248:249], off
	global_load_dwordx4 v[172:175], v[248:249], off offset:64
	global_load_dwordx4 v[176:179], v[248:249], off offset:512
	global_load_dwordx4 v[204:207], v[248:249], off offset:576
	v_lshl_add_u64 v[248:249], v[248:249], 0, s[94:95]
	global_load_dwordx4 v[208:211], v[248:249], off
	global_load_dwordx4 v[212:215], v[248:249], off offset:64
	global_load_dwordx4 v[216:219], v[248:249], off offset:512
	global_load_dwordx4 v[220:223], v[248:249], off offset:576
	v_lshl_add_u64 v[248:249], v[248:249], 0, s[94:95]
	global_load_dwordx4 v[224:227], v[248:249], off
	global_load_dwordx4 v[228:231], v[248:249], off offset:64
	global_load_dwordx4 v[232:235], v[248:249], off offset:512
	global_load_dwordx4 v[236:239], v[248:249], off offset:576
	v_lshl_add_u64 v[248:249], v[248:249], 0, s[94:95]
	global_load_dwordx4 v[240:243], v[248:249], off
	global_load_dwordx4 v[244:247], v[248:249], off offset:64
	s_waitcnt vmcnt(13)
	v_pk_mul_f32 v[154:155], v[154:155], 0.5 op_sel_hi:[1,0]
	v_pk_mul_f32 v[152:153], v[152:153], 0.5 op_sel_hi:[1,0]
	v_pk_mul_f32 v[158:159], v[158:159], 0.5 op_sel_hi:[1,0]
	v_pk_mul_f32 v[156:157], v[156:157], 0.5 op_sel_hi:[1,0]
	v_pk_mul_f32 v[162:163], v[162:163], 0.5 op_sel_hi:[1,0]
	v_pk_mul_f32 v[160:161], v[160:161], 0.5 op_sel_hi:[1,0]
	v_pk_mul_f32 v[166:167], v[166:167], 0.5 op_sel_hi:[1,0]
	v_pk_mul_f32 v[164:165], v[164:165], 0.5 op_sel_hi:[1,0]
	v_pk_fma_f32 v[126:127], v[126:127], v[154:155], v[170:171]
	v_pk_fma_f32 v[124:125], v[124:125], v[152:153], v[168:169]
	global_load_dwordx4 v[168:171], v[248:249], off offset:512
	s_waitcnt vmcnt(13)
	v_pk_fma_f32 v[122:123], v[122:123], v[158:159], v[174:175]
	v_pk_fma_f32 v[120:121], v[120:121], v[156:157], v[172:173]
	global_load_dwordx4 v[172:175], v[248:249], off offset:576
	s_waitcnt vmcnt(13)
	v_pk_fma_f32 v[94:95], v[94:95], v[162:163], v[178:179]
	v_pk_fma_f32 v[92:93], v[92:93], v[160:161], v[176:177]
	v_lshl_add_u64 v[248:249], v[248:249], 0, s[96:97]
	global_load_dwordx4 v[176:179], v[248:249], off
	s_waitcnt vmcnt(13)
	v_pk_fma_f32 v[90:91], v[90:91], v[166:167], v[206:207]
	v_pk_fma_f32 v[88:89], v[88:89], v[164:165], v[204:205]
	global_load_dwordx4 v[204:207], v[248:249], off offset:64
	s_waitcnt vmcnt(13)
	v_pk_fma_f32 v[118:119], v[118:119], v[154:155], v[210:211]
	v_pk_fma_f32 v[116:117], v[116:117], v[152:153], v[208:209]
	global_load_dwordx4 v[208:211], v[248:249], off offset:512
	s_waitcnt vmcnt(13)
	v_pk_fma_f32 v[114:115], v[114:115], v[158:159], v[214:215]
	v_pk_fma_f32 v[112:113], v[112:113], v[156:157], v[212:213]
	global_load_dwordx4 v[212:215], v[248:249], off offset:576
	s_waitcnt vmcnt(13)
	v_pk_fma_f32 v[86:87], v[86:87], v[162:163], v[218:219]
	v_pk_fma_f32 v[84:85], v[84:85], v[160:161], v[216:217]
	v_lshl_add_u64 v[248:249], v[248:249], 0, s[94:95]
	global_load_dwordx4 v[216:219], v[248:249], off
	s_waitcnt vmcnt(13)
	v_pk_fma_f32 v[82:83], v[82:83], v[166:167], v[222:223]
	v_pk_fma_f32 v[80:81], v[80:81], v[164:165], v[220:221]
	global_load_dwordx4 v[220:223], v[248:249], off offset:64
	s_waitcnt vmcnt(13)
	v_pk_fma_f32 v[110:111], v[110:111], v[154:155], v[226:227]
	v_pk_fma_f32 v[108:109], v[108:109], v[152:153], v[224:225]
	global_load_dwordx4 v[224:227], v[248:249], off offset:512
	s_waitcnt vmcnt(13)
	v_pk_fma_f32 v[106:107], v[106:107], v[158:159], v[230:231]
	v_pk_fma_f32 v[104:105], v[104:105], v[156:157], v[228:229]
	global_load_dwordx4 v[228:231], v[248:249], off offset:576
	s_waitcnt vmcnt(13)
	v_pk_fma_f32 v[78:79], v[78:79], v[162:163], v[234:235]
	v_pk_fma_f32 v[76:77], v[76:77], v[160:161], v[232:233]
	v_lshl_add_u64 v[248:249], v[248:249], 0, s[94:95]
	global_load_dwordx4 v[232:235], v[248:249], off
	s_waitcnt vmcnt(13)
	v_pk_fma_f32 v[74:75], v[74:75], v[166:167], v[238:239]
	v_pk_fma_f32 v[72:73], v[72:73], v[164:165], v[236:237]
	global_load_dwordx4 v[236:239], v[248:249], off offset:64
	s_waitcnt vmcnt(13)
	v_pk_fma_f32 v[102:103], v[102:103], v[154:155], v[242:243]
	v_pk_fma_f32 v[100:101], v[100:101], v[152:153], v[240:241]
	global_load_dwordx4 v[240:243], v[248:249], off offset:512
	s_waitcnt vmcnt(13)
	v_pk_fma_f32 v[98:99], v[98:99], v[158:159], v[246:247]
	v_pk_fma_f32 v[96:97], v[96:97], v[156:157], v[244:245]
	global_load_dwordx4 v[244:247], v[248:249], off offset:576
	s_waitcnt vmcnt(13)
	v_pk_fma_f32 v[70:71], v[70:71], v[162:163], v[170:171]
	v_pk_fma_f32 v[68:69], v[68:69], v[160:161], v[168:169]
	v_lshl_add_u64 v[248:249], v[248:249], 0, s[94:95]
	global_load_dwordx4 v[168:171], v[248:249], off
	s_waitcnt vmcnt(13)
	v_pk_fma_f32 v[66:67], v[66:67], v[166:167], v[174:175]
	v_pk_fma_f32 v[64:65], v[64:65], v[164:165], v[172:173]
	global_load_dwordx4 v[172:175], v[248:249], off offset:64
	s_waitcnt vmcnt(13)
	v_pk_fma_f32 v[62:63], v[62:63], v[154:155], v[178:179]
	v_pk_fma_f32 v[60:61], v[60:61], v[152:153], v[176:177]
	global_load_dwordx4 v[176:179], v[248:249], off offset:512
	s_waitcnt vmcnt(13)
	v_pk_fma_f32 v[58:59], v[58:59], v[158:159], v[206:207]
	v_pk_fma_f32 v[56:57], v[56:57], v[156:157], v[204:205]
	global_load_dwordx4 v[204:207], v[248:249], off offset:576
	s_waitcnt vmcnt(13)
	v_pk_fma_f32 v[30:31], v[30:31], v[162:163], v[210:211]
	v_pk_fma_f32 v[28:29], v[28:29], v[160:161], v[208:209]
	s_waitcnt vmcnt(12)
	v_pk_fma_f32 v[26:27], v[26:27], v[166:167], v[214:215]
	v_pk_fma_f32 v[24:25], v[24:25], v[164:165], v[212:213]
	s_waitcnt vmcnt(11)
	v_pk_fma_f32 v[54:55], v[54:55], v[154:155], v[218:219]
	v_pk_fma_f32 v[52:53], v[52:53], v[152:153], v[216:217]
	s_waitcnt vmcnt(10)
	v_pk_fma_f32 v[50:51], v[50:51], v[158:159], v[222:223]
	v_pk_fma_f32 v[48:49], v[48:49], v[156:157], v[220:221]
	s_waitcnt vmcnt(9)
	v_pk_fma_f32 v[22:23], v[22:23], v[162:163], v[226:227]
	v_pk_fma_f32 v[20:21], v[20:21], v[160:161], v[224:225]
	s_waitcnt vmcnt(8)
	v_pk_fma_f32 v[18:19], v[18:19], v[166:167], v[230:231]
	v_pk_fma_f32 v[16:17], v[16:17], v[164:165], v[228:229]
	s_waitcnt vmcnt(7)
	v_pk_fma_f32 v[46:47], v[46:47], v[154:155], v[234:235]
	v_pk_fma_f32 v[44:45], v[44:45], v[152:153], v[232:233]
	s_waitcnt vmcnt(6)
	v_pk_fma_f32 v[42:43], v[42:43], v[158:159], v[238:239]
	v_pk_fma_f32 v[40:41], v[40:41], v[156:157], v[236:237]
	s_waitcnt vmcnt(5)
	v_pk_fma_f32 v[14:15], v[14:15], v[162:163], v[242:243]
	v_pk_fma_f32 v[12:13], v[12:13], v[160:161], v[240:241]
	s_waitcnt vmcnt(4)
	v_pk_fma_f32 v[10:11], v[10:11], v[166:167], v[246:247]
	v_pk_fma_f32 v[8:9], v[8:9], v[164:165], v[244:245]
	s_waitcnt vmcnt(3)
	v_pk_fma_f32 v[38:39], v[38:39], v[154:155], v[170:171]
	v_pk_fma_f32 v[36:37], v[36:37], v[152:153], v[168:169]
	s_waitcnt vmcnt(2)
	v_pk_fma_f32 v[34:35], v[34:35], v[158:159], v[174:175]
	v_pk_fma_f32 v[32:33], v[32:33], v[156:157], v[172:173]
	s_waitcnt vmcnt(1)
	v_pk_fma_f32 v[6:7], v[6:7], v[162:163], v[178:179]
	v_pk_fma_f32 v[4:5], v[4:5], v[160:161], v[176:177]
	s_waitcnt vmcnt(0)
	v_pk_fma_f32 v[2:3], v[2:3], v[166:167], v[206:207]
	v_pk_fma_f32 v[0:1], v[0:1], v[164:165], v[204:205]
	v_and_b32_e32 v204, 63, v131
	v_lshrrev_b32_e32 v205, 6, v131
	v_and_b32_e32 v206, 15, v204
	v_lshrrev_b32_e32 v207, 4, v204
	v_lshrrev_b32_e32 v208, 2, v205
	v_and_b32_e32 v209, 3, v205
	v_lshl_add_u32 v210, v208, 6, v206
	v_lshlrev_b32_e32 v210, 12, v210
	v_lshl_add_u32 v210, v209, 7, v210
	v_lshl_add_u32 v210, v207, 4, v210
	v_sub_co_u32_e32 v212, vcc, v140, v210
	s_nop 0
	v_subbrev_co_u32_e32 v213, vcc, 0, v141, vcc
	v_lshl_add_u32 v214, v209, 3, v207
	v_xor_b32_e32 v214, v214, v206
	v_lshlrev_b32_e32 v214, 4, v214
	v_lshl_add_u32 v214, v206, 9, v214
	v_lshl_add_u32 v214, v208, 16, v214
	v_xor_b32_e32 v215, 64, v214
	v_lshrrev_b32_e32 v216, 5, v204
	v_and_b32_e32 v217, 31, v204
	v_and_b32_e32 v218, 3, v205
	v_lshl_add_u32 v218, v218, 4, v216
	v_lshlrev_b32_e32 v218, 9, v218
	v_lshrrev_b32_e32 v219, 2, v205
	v_lshl_add_u32 v218, v219, 16, v218
	v_xor_b32_e32 v219, v217, v216
	v_lshl_add_u32 v218, v219, 4, v218
	v_mov_b32_e32 v220, v218
	v_xor_b32_e32 v221, 32, v218
	v_xor_b32_e32 v222, 64, v218
	v_xor_b32_e32 v223, 0x60, v218
	v_xor_b32_e32 v224, 0x80, v218
	v_xor_b32_e32 v225, 0xa0, v218
	v_xor_b32_e32 v226, 0xc0, v218
	v_xor_b32_e32 v227, 0xe0, v218
	v_lshl_add_u32 v228, v205, 4, v216
	v_lshlrev_b32_e32 v228, 12, v228
	v_lshl_add_u32 v228, v217, 4, v228
	v_mov_b32_e32 v229, 0
	v_lshl_add_u64 v[230:231], v[212:213], 0, v[228:229]
	s_mov_b64 s[94:95], 0x80000
	s_mov_b64 s[96:97], 0x2000
	ds_write_b128 v214, v[124:127] offset:32800
	ds_write_b128 v215, v[120:123] offset:32800
	ds_write_b128 v214, v[116:119] offset:40992
	ds_write_b128 v215, v[112:115] offset:40992
	ds_write_b128 v214, v[108:111] offset:49184
	ds_write_b128 v215, v[104:107] offset:49184
	ds_write_b128 v214, v[100:103] offset:57376
	ds_write_b128 v215, v[96:99] offset:57376
	s_waitcnt lgkmcnt(0)
	s_barrier
	ds_read_b128 v[152:155], v220 offset:32800
	ds_read_b128 v[156:159], v221 offset:33824
	ds_read_b128 v[160:163], v222 offset:34848
	ds_read_b128 v[164:167], v223 offset:35872
	ds_read_b128 v[168:171], v224 offset:36896
	ds_read_b128 v[172:175], v225 offset:37920
	ds_read_b128 v[176:179], v226 offset:38944
	ds_read_b128 v[236:239], v227 offset:39968
	v_mov_b64_e32 v[232:233], v[230:231]
	s_waitcnt lgkmcnt(7)
	global_store_dwordx4 v[232:233], v[152:155], off sc1
	v_lshl_add_u64 v[232:233], v[232:233], 0, s[96:97]
	s_waitcnt lgkmcnt(6)
	global_store_dwordx4 v[232:233], v[156:159], off sc1
	v_lshl_add_u64 v[232:233], v[232:233], 0, s[96:97]
	s_waitcnt lgkmcnt(5)
	global_store_dwordx4 v[232:233], v[160:163], off sc1
	v_lshl_add_u64 v[232:233], v[232:233], 0, s[96:97]
	s_waitcnt lgkmcnt(4)
	global_store_dwordx4 v[232:233], v[164:167], off sc1
	v_lshl_add_u64 v[232:233], v[232:233], 0, s[96:97]
	s_waitcnt lgkmcnt(3)
	global_store_dwordx4 v[232:233], v[168:171], off sc1
	v_lshl_add_u64 v[232:233], v[232:233], 0, s[96:97]
	s_waitcnt lgkmcnt(2)
	global_store_dwordx4 v[232:233], v[172:175], off sc1
	v_lshl_add_u64 v[232:233], v[232:233], 0, s[96:97]
	s_waitcnt lgkmcnt(1)
	global_store_dwordx4 v[232:233], v[176:179], off sc1
	v_lshl_add_u64 v[232:233], v[232:233], 0, s[96:97]
	s_waitcnt lgkmcnt(0)
	global_store_dwordx4 v[232:233], v[236:239], off sc1
	s_barrier
	ds_write_b128 v214, v[92:95] offset:32800
	ds_write_b128 v215, v[88:91] offset:32800
	ds_write_b128 v214, v[84:87] offset:40992
	ds_write_b128 v215, v[80:83] offset:40992
	ds_write_b128 v214, v[76:79] offset:49184
	ds_write_b128 v215, v[72:75] offset:49184
	ds_write_b128 v214, v[68:71] offset:57376
	ds_write_b128 v215, v[64:67] offset:57376
	s_waitcnt lgkmcnt(0)
	s_barrier
	ds_read_b128 v[152:155], v220 offset:32800
	ds_read_b128 v[156:159], v221 offset:33824
	ds_read_b128 v[160:163], v222 offset:34848
	ds_read_b128 v[164:167], v223 offset:35872
	ds_read_b128 v[168:171], v224 offset:36896
	ds_read_b128 v[172:175], v225 offset:37920
	ds_read_b128 v[176:179], v226 offset:38944
	ds_read_b128 v[236:239], v227 offset:39968
	v_mov_b64_e32 v[232:233], v[230:231]
	s_waitcnt lgkmcnt(7)
	global_store_dwordx4 v[232:233], v[152:155], off offset:512 sc1
	v_lshl_add_u64 v[232:233], v[232:233], 0, s[96:97]
	s_waitcnt lgkmcnt(6)
	global_store_dwordx4 v[232:233], v[156:159], off offset:512 sc1
	v_lshl_add_u64 v[232:233], v[232:233], 0, s[96:97]
	s_waitcnt lgkmcnt(5)
	global_store_dwordx4 v[232:233], v[160:163], off offset:512 sc1
	v_lshl_add_u64 v[232:233], v[232:233], 0, s[96:97]
	s_waitcnt lgkmcnt(4)
	global_store_dwordx4 v[232:233], v[164:167], off offset:512 sc1
	v_lshl_add_u64 v[232:233], v[232:233], 0, s[96:97]
	s_waitcnt lgkmcnt(3)
	global_store_dwordx4 v[232:233], v[168:171], off offset:512 sc1
	v_lshl_add_u64 v[232:233], v[232:233], 0, s[96:97]
	s_waitcnt lgkmcnt(2)
	global_store_dwordx4 v[232:233], v[172:175], off offset:512 sc1
	v_lshl_add_u64 v[232:233], v[232:233], 0, s[96:97]
	s_waitcnt lgkmcnt(1)
	global_store_dwordx4 v[232:233], v[176:179], off offset:512 sc1
	v_lshl_add_u64 v[232:233], v[232:233], 0, s[96:97]
	s_waitcnt lgkmcnt(0)
	global_store_dwordx4 v[232:233], v[236:239], off offset:512 sc1
	s_barrier
	ds_write_b128 v214, v[60:63] offset:32800
	ds_write_b128 v215, v[56:59] offset:32800
	ds_write_b128 v214, v[52:55] offset:40992
	ds_write_b128 v215, v[48:51] offset:40992
	ds_write_b128 v214, v[44:47] offset:49184
	ds_write_b128 v215, v[40:43] offset:49184
	ds_write_b128 v214, v[36:39] offset:57376
	ds_write_b128 v215, v[32:35] offset:57376
	s_waitcnt lgkmcnt(0)
	s_barrier
	ds_read_b128 v[152:155], v220 offset:32800
	ds_read_b128 v[156:159], v221 offset:33824
	ds_read_b128 v[160:163], v222 offset:34848
	ds_read_b128 v[164:167], v223 offset:35872
	ds_read_b128 v[168:171], v224 offset:36896
	ds_read_b128 v[172:175], v225 offset:37920
	ds_read_b128 v[176:179], v226 offset:38944
	ds_read_b128 v[236:239], v227 offset:39968
	v_lshl_add_u64 v[232:233], v[230:231], 0, s[94:95]
	s_waitcnt lgkmcnt(7)
	global_store_dwordx4 v[232:233], v[152:155], off sc1
	v_lshl_add_u64 v[232:233], v[232:233], 0, s[96:97]
	s_waitcnt lgkmcnt(6)
	global_store_dwordx4 v[232:233], v[156:159], off sc1
	v_lshl_add_u64 v[232:233], v[232:233], 0, s[96:97]
	s_waitcnt lgkmcnt(5)
	global_store_dwordx4 v[232:233], v[160:163], off sc1
	v_lshl_add_u64 v[232:233], v[232:233], 0, s[96:97]
	s_waitcnt lgkmcnt(4)
	global_store_dwordx4 v[232:233], v[164:167], off sc1
	v_lshl_add_u64 v[232:233], v[232:233], 0, s[96:97]
	s_waitcnt lgkmcnt(3)
	global_store_dwordx4 v[232:233], v[168:171], off sc1
	v_lshl_add_u64 v[232:233], v[232:233], 0, s[96:97]
	s_waitcnt lgkmcnt(2)
	global_store_dwordx4 v[232:233], v[172:175], off sc1
	v_lshl_add_u64 v[232:233], v[232:233], 0, s[96:97]
	s_waitcnt lgkmcnt(1)
	global_store_dwordx4 v[232:233], v[176:179], off sc1
	v_lshl_add_u64 v[232:233], v[232:233], 0, s[96:97]
	s_waitcnt lgkmcnt(0)
	global_store_dwordx4 v[232:233], v[236:239], off sc1
	s_barrier
	ds_write_b128 v214, v[28:31] offset:32800
	ds_write_b128 v215, v[24:27] offset:32800
	ds_write_b128 v214, v[20:23] offset:40992
	ds_write_b128 v215, v[16:19] offset:40992
	ds_write_b128 v214, v[12:15] offset:49184
	ds_write_b128 v215, v[8:11] offset:49184
	ds_write_b128 v214, v[4:7] offset:57376
	ds_write_b128 v215, v[0:3] offset:57376
	s_waitcnt lgkmcnt(0)
	s_barrier
	ds_read_b128 v[152:155], v220 offset:32800
	ds_read_b128 v[156:159], v221 offset:33824
	ds_read_b128 v[160:163], v222 offset:34848
	ds_read_b128 v[164:167], v223 offset:35872
	ds_read_b128 v[168:171], v224 offset:36896
	ds_read_b128 v[172:175], v225 offset:37920
	ds_read_b128 v[176:179], v226 offset:38944
	ds_read_b128 v[236:239], v227 offset:39968
	v_lshl_add_u64 v[232:233], v[230:231], 0, s[94:95]
	s_waitcnt lgkmcnt(7)
	global_store_dwordx4 v[232:233], v[152:155], off offset:512 sc1
	v_lshl_add_u64 v[232:233], v[232:233], 0, s[96:97]
	s_waitcnt lgkmcnt(6)
	global_store_dwordx4 v[232:233], v[156:159], off offset:512 sc1
	v_lshl_add_u64 v[232:233], v[232:233], 0, s[96:97]
	s_waitcnt lgkmcnt(5)
	global_store_dwordx4 v[232:233], v[160:163], off offset:512 sc1
	v_lshl_add_u64 v[232:233], v[232:233], 0, s[96:97]
	s_waitcnt lgkmcnt(4)
	global_store_dwordx4 v[232:233], v[164:167], off offset:512 sc1
	v_lshl_add_u64 v[232:233], v[232:233], 0, s[96:97]
	s_waitcnt lgkmcnt(3)
	global_store_dwordx4 v[232:233], v[168:171], off offset:512 sc1
	v_lshl_add_u64 v[232:233], v[232:233], 0, s[96:97]
	s_waitcnt lgkmcnt(2)
	global_store_dwordx4 v[232:233], v[172:175], off offset:512 sc1
	v_lshl_add_u64 v[232:233], v[232:233], 0, s[96:97]
	s_waitcnt lgkmcnt(1)
	global_store_dwordx4 v[232:233], v[176:179], off offset:512 sc1
	v_lshl_add_u64 v[232:233], v[232:233], 0, s[96:97]
	s_waitcnt lgkmcnt(0)
	global_store_dwordx4 v[232:233], v[236:239], off offset:512 sc1
	s_barrier
	s_mov_b32 s26, s28
	s_mov_b32 s27, s29
	s_andn2_b64 vcc, exec, s[14:15]
	s_cbranch_vccz .LBB0_811

.LBB0_1831:
	v_add_u32_e32 v146, s26, v133
	v_min_i32_e32 v144, 0x8000, v146
	v_readlane_b32 s48, v251, 19
	v_ashrrev_i32_e32 v144, 12, v144
	v_readlane_b32 s52, v251, 23
	v_readlane_b32 s53, v251, 24
	v_readlane_b32 s54, v251, 25
	v_readlane_b32 s55, v251, 26
	v_readlane_b32 s56, v251, 27
	v_readlane_b32 s57, v251, 28
	v_readlane_b32 s58, v251, 29
	v_readlane_b32 s59, v251, 30
	v_add_u32_e32 v140, s25, v149
	s_mov_b32 s11, 0x8000
	v_mul_i32_i24_e32 v144, 0x2400, v144
	v_readlane_b32 s60, v251, 31
	v_readlane_b32 s61, v251, 32
	v_readlane_b32 s62, v251, 33
	v_readlane_b32 s63, v251, 34
	s_mov_b64 s[52:53], s[56:57]
	v_readlane_b32 s30, v254, 27
	v_ashrrev_i32_e32 v141, 31, v140
	v_add_u32_e32 v142, 0xffff8000, v146
	v_ashrrev_i32_e32 v143, 31, v146
	v_cmp_gt_i32_e32 vcc, s11, v146
	v_ashrrev_i32_e32 v145, 31, v144
	s_mov_b64 s[54:55], s[58:59]
	v_readlane_b32 s31, v254, 28
	v_cndmask_b32_e32 v143, 0, v143, vcc
	v_cndmask_b32_e32 v142, v142, v146, vcc
	v_mov_b32_e32 v147, s55
	v_mov_b32_e32 v151, s53
	v_mov_b32_e32 v152, s54
	v_mov_b32_e32 v153, s52
	v_lshl_add_u64 v[144:145], v[144:145], 2, s[30:31]
	v_lshlrev_b64 v[140:141], 2, v[140:141]
	v_lshlrev_b64 v[142:143], 12, v[142:143]
	v_cndmask_b32_e32 v155, v147, v151, vcc
	v_cndmask_b32_e32 v154, v152, v153, vcc
	v_lshl_add_u64 v[144:145], v[144:145], 0, v[140:141]
	s_movk_i32 s27, 0x5000
	v_lshl_add_u64 v[142:143], v[154:155], 0, v[142:143]
	v_add_co_u32_e32 v154, vcc, s27, v144
	v_lshl_add_u64 v[142:143], v[142:143], 0, v[140:141]
	s_nop 0
	v_addc_co_u32_e32 v155, vcc, 0, v145, vcc
	s_nop 0
	s_mov_b64 s[28:29], 0x5000
	v_lshl_add_u64 v[144:145], v[144:145], 0, s[28:29]
	s_movk_i32 s13, 0x7ff0
	v_cmp_gt_i32_e32 vcc, s13, v146
	s_movk_i32 s25, 0x7fe0
	s_movk_i32 s26, 0x7fd0
	v_readlane_b32 s49, v251, 20
	v_readlane_b32 s50, v251, 21
	v_readlane_b32 s51, v251, 22
	s_mov_b64 s[56:57], s[60:61]
	s_mov_b64 s[58:59], s[62:63]
	s_mov_b64 s[94:95], 0x10000
	s_mov_b64 s[96:97], 0x50000
	global_load_dwordx4 v[152:155], v[144:145], off
	global_load_dwordx4 v[156:159], v[144:145], off offset:64
	global_load_dwordx4 v[160:163], v[144:145], off offset:512
	global_load_dwordx4 v[164:167], v[144:145], off offset:576
	v_mov_b64_e32 v[248:249], v[142:143]
	v_mov_b64_e32 v[140:141], v[142:143]
	global_load_dwordx4 v[168:171], v[248:249], off
	global_load_dwordx4 v[172:175], v[248:249], off offset:64
	global_load_dwordx4 v[176:179], v[248:249], off offset:512
	global_load_dwordx4 v[204:207], v[248:249], off offset:576
	v_lshl_add_u64 v[248:249], v[248:249], 0, s[94:95]
	global_load_dwordx4 v[208:211], v[248:249], off
	global_load_dwordx4 v[212:215], v[248:249], off offset:64
	global_load_dwordx4 v[216:219], v[248:249], off offset:512
	global_load_dwordx4 v[220:223], v[248:249], off offset:576
	v_lshl_add_u64 v[248:249], v[248:249], 0, s[94:95]
	global_load_dwordx4 v[224:227], v[248:249], off
	global_load_dwordx4 v[228:231], v[248:249], off offset:64
	global_load_dwordx4 v[232:235], v[248:249], off offset:512
	global_load_dwordx4 v[236:239], v[248:249], off offset:576
	v_lshl_add_u64 v[248:249], v[248:249], 0, s[94:95]
	global_load_dwordx4 v[240:243], v[248:249], off
	global_load_dwordx4 v[244:247], v[248:249], off offset:64
	s_waitcnt vmcnt(13)
	v_pk_fma_f32 v[126:127], v[126:127], v[154:155], v[170:171]
	v_pk_fma_f32 v[124:125], v[124:125], v[152:153], v[168:169]
	global_load_dwordx4 v[168:171], v[248:249], off offset:512
	s_waitcnt vmcnt(13)
	v_pk_fma_f32 v[122:123], v[122:123], v[158:159], v[174:175]
	v_pk_fma_f32 v[120:121], v[120:121], v[156:157], v[172:173]
	global_load_dwordx4 v[172:175], v[248:249], off offset:576
	s_waitcnt vmcnt(13)
	v_pk_fma_f32 v[94:95], v[94:95], v[162:163], v[178:179]
	v_pk_fma_f32 v[92:93], v[92:93], v[160:161], v[176:177]
	v_lshl_add_u64 v[248:249], v[248:249], 0, s[96:97]
	global_load_dwordx4 v[176:179], v[248:249], off
	s_waitcnt vmcnt(13)
	v_pk_fma_f32 v[90:91], v[90:91], v[166:167], v[206:207]
	v_pk_fma_f32 v[88:89], v[88:89], v[164:165], v[204:205]
	global_load_dwordx4 v[204:207], v[248:249], off offset:64
	s_waitcnt vmcnt(13)
	v_pk_fma_f32 v[118:119], v[118:119], v[154:155], v[210:211]
	v_pk_fma_f32 v[116:117], v[116:117], v[152:153], v[208:209]
	global_load_dwordx4 v[208:211], v[248:249], off offset:512
	s_waitcnt vmcnt(13)
	v_pk_fma_f32 v[114:115], v[114:115], v[158:159], v[214:215]
	v_pk_fma_f32 v[112:113], v[112:113], v[156:157], v[212:213]
	global_load_dwordx4 v[212:215], v[248:249], off offset:576
	s_waitcnt vmcnt(13)
	v_pk_fma_f32 v[86:87], v[86:87], v[162:163], v[218:219]
	v_pk_fma_f32 v[84:85], v[84:85], v[160:161], v[216:217]
	v_lshl_add_u64 v[248:249], v[248:249], 0, s[94:95]
	global_load_dwordx4 v[216:219], v[248:249], off
	s_waitcnt vmcnt(13)
	v_pk_fma_f32 v[82:83], v[82:83], v[166:167], v[222:223]
	v_pk_fma_f32 v[80:81], v[80:81], v[164:165], v[220:221]
	global_load_dwordx4 v[220:223], v[248:249], off offset:64
	s_waitcnt vmcnt(13)
	v_pk_fma_f32 v[110:111], v[110:111], v[154:155], v[226:227]
	v_pk_fma_f32 v[108:109], v[108:109], v[152:153], v[224:225]
	global_load_dwordx4 v[224:227], v[248:249], off offset:512
	s_waitcnt vmcnt(13)
	v_pk_fma_f32 v[106:107], v[106:107], v[158:159], v[230:231]
	v_pk_fma_f32 v[104:105], v[104:105], v[156:157], v[228:229]
	global_load_dwordx4 v[228:231], v[248:249], off offset:576
	s_waitcnt vmcnt(13)
	v_pk_fma_f32 v[78:79], v[78:79], v[162:163], v[234:235]
	v_pk_fma_f32 v[76:77], v[76:77], v[160:161], v[232:233]
	v_lshl_add_u64 v[248:249], v[248:249], 0, s[94:95]
	global_load_dwordx4 v[232:235], v[248:249], off
	s_waitcnt vmcnt(13)
	v_pk_fma_f32 v[74:75], v[74:75], v[166:167], v[238:239]
	v_pk_fma_f32 v[72:73], v[72:73], v[164:165], v[236:237]
	global_load_dwordx4 v[236:239], v[248:249], off offset:64
	s_waitcnt vmcnt(13)
	v_pk_fma_f32 v[102:103], v[102:103], v[154:155], v[242:243]
	v_pk_fma_f32 v[100:101], v[100:101], v[152:153], v[240:241]
	global_load_dwordx4 v[240:243], v[248:249], off offset:512
	s_waitcnt vmcnt(13)
	v_pk_fma_f32 v[98:99], v[98:99], v[158:159], v[246:247]
	v_pk_fma_f32 v[96:97], v[96:97], v[156:157], v[244:245]
	global_load_dwordx4 v[244:247], v[248:249], off offset:576
	s_waitcnt vmcnt(13)
	v_pk_fma_f32 v[70:71], v[70:71], v[162:163], v[170:171]
	v_pk_fma_f32 v[68:69], v[68:69], v[160:161], v[168:169]
	v_lshl_add_u64 v[248:249], v[248:249], 0, s[94:95]
	global_load_dwordx4 v[168:171], v[248:249], off
	s_waitcnt vmcnt(13)
	v_pk_fma_f32 v[66:67], v[66:67], v[166:167], v[174:175]
	v_pk_fma_f32 v[64:65], v[64:65], v[164:165], v[172:173]
	global_load_dwordx4 v[172:175], v[248:249], off offset:64
	s_waitcnt vmcnt(13)
	v_pk_fma_f32 v[62:63], v[62:63], v[154:155], v[178:179]
	v_pk_fma_f32 v[60:61], v[60:61], v[152:153], v[176:177]
	global_load_dwordx4 v[176:179], v[248:249], off offset:512
	s_waitcnt vmcnt(13)
	v_pk_fma_f32 v[58:59], v[58:59], v[158:159], v[206:207]
	v_pk_fma_f32 v[56:57], v[56:57], v[156:157], v[204:205]
	global_load_dwordx4 v[204:207], v[248:249], off offset:576
	s_waitcnt vmcnt(13)
	v_pk_fma_f32 v[30:31], v[30:31], v[162:163], v[210:211]
	v_pk_fma_f32 v[28:29], v[28:29], v[160:161], v[208:209]
	s_waitcnt vmcnt(12)
	v_pk_fma_f32 v[26:27], v[26:27], v[166:167], v[214:215]
	v_pk_fma_f32 v[24:25], v[24:25], v[164:165], v[212:213]
	s_waitcnt vmcnt(11)
	v_pk_fma_f32 v[54:55], v[54:55], v[154:155], v[218:219]
	v_pk_fma_f32 v[52:53], v[52:53], v[152:153], v[216:217]
	s_waitcnt vmcnt(10)
	v_pk_fma_f32 v[50:51], v[50:51], v[158:159], v[222:223]
	v_pk_fma_f32 v[48:49], v[48:49], v[156:157], v[220:221]
	s_waitcnt vmcnt(9)
	v_pk_fma_f32 v[22:23], v[22:23], v[162:163], v[226:227]
	v_pk_fma_f32 v[20:21], v[20:21], v[160:161], v[224:225]
	s_waitcnt vmcnt(8)
	v_pk_fma_f32 v[18:19], v[18:19], v[166:167], v[230:231]
	v_pk_fma_f32 v[16:17], v[16:17], v[164:165], v[228:229]
	s_waitcnt vmcnt(7)
	v_pk_fma_f32 v[46:47], v[46:47], v[154:155], v[234:235]
	v_pk_fma_f32 v[44:45], v[44:45], v[152:153], v[232:233]
	s_waitcnt vmcnt(6)
	v_pk_fma_f32 v[42:43], v[42:43], v[158:159], v[238:239]
	v_pk_fma_f32 v[40:41], v[40:41], v[156:157], v[236:237]
	s_waitcnt vmcnt(5)
	v_pk_fma_f32 v[14:15], v[14:15], v[162:163], v[242:243]
	v_pk_fma_f32 v[12:13], v[12:13], v[160:161], v[240:241]
	s_waitcnt vmcnt(4)
	v_pk_fma_f32 v[10:11], v[10:11], v[166:167], v[246:247]
	v_pk_fma_f32 v[8:9], v[8:9], v[164:165], v[244:245]
	s_waitcnt vmcnt(3)
	v_pk_fma_f32 v[38:39], v[38:39], v[154:155], v[170:171]
	v_pk_fma_f32 v[36:37], v[36:37], v[152:153], v[168:169]
	s_waitcnt vmcnt(2)
	v_pk_fma_f32 v[34:35], v[34:35], v[158:159], v[174:175]
	v_pk_fma_f32 v[32:33], v[32:33], v[156:157], v[172:173]
	s_waitcnt vmcnt(1)
	v_pk_fma_f32 v[6:7], v[6:7], v[162:163], v[178:179]
	v_pk_fma_f32 v[4:5], v[4:5], v[160:161], v[176:177]
	s_waitcnt vmcnt(0)
	v_pk_fma_f32 v[2:3], v[2:3], v[166:167], v[206:207]
	v_pk_fma_f32 v[0:1], v[0:1], v[164:165], v[204:205]
	v_and_b32_e32 v204, 63, v131
	v_lshrrev_b32_e32 v205, 6, v131
	v_and_b32_e32 v206, 15, v204
	v_lshrrev_b32_e32 v207, 4, v204
	v_lshrrev_b32_e32 v208, 2, v205
	v_and_b32_e32 v209, 3, v205
	v_lshl_add_u32 v210, v208, 6, v206
	v_lshlrev_b32_e32 v210, 12, v210
	v_lshl_add_u32 v210, v209, 7, v210
	v_lshl_add_u32 v210, v207, 4, v210
	v_sub_co_u32_e32 v212, vcc, v140, v210
	s_nop 0
	v_subbrev_co_u32_e32 v213, vcc, 0, v141, vcc
	v_lshl_add_u32 v214, v209, 3, v207
	v_xor_b32_e32 v214, v214, v206
	v_lshlrev_b32_e32 v214, 4, v214
	v_lshl_add_u32 v214, v206, 9, v214
	v_lshl_add_u32 v214, v208, 16, v214
	v_xor_b32_e32 v215, 64, v214
	v_lshrrev_b32_e32 v216, 5, v204
	v_and_b32_e32 v217, 31, v204
	v_and_b32_e32 v218, 3, v205
	v_lshl_add_u32 v218, v218, 4, v216
	v_lshlrev_b32_e32 v218, 9, v218
	v_lshrrev_b32_e32 v219, 2, v205
	v_lshl_add_u32 v218, v219, 16, v218
	v_xor_b32_e32 v219, v217, v216
	v_lshl_add_u32 v218, v219, 4, v218
	v_mov_b32_e32 v220, v218
	v_xor_b32_e32 v221, 32, v218
	v_xor_b32_e32 v222, 64, v218
	v_xor_b32_e32 v223, 0x60, v218
	v_xor_b32_e32 v224, 0x80, v218
	v_xor_b32_e32 v225, 0xa0, v218
	v_xor_b32_e32 v226, 0xc0, v218
	v_xor_b32_e32 v227, 0xe0, v218
	v_lshl_add_u32 v228, v205, 4, v216
	v_lshlrev_b32_e32 v228, 12, v228
	v_lshl_add_u32 v228, v217, 4, v228
	v_mov_b32_e32 v229, 0
	v_lshl_add_u64 v[230:231], v[212:213], 0, v[228:229]
	s_mov_b64 s[94:95], 0x80000
	s_mov_b64 s[96:97], 0x2000
	ds_write_b128 v214, v[124:127] offset:32800
	ds_write_b128 v215, v[120:123] offset:32800
	ds_write_b128 v214, v[116:119] offset:40992
	ds_write_b128 v215, v[112:115] offset:40992
	ds_write_b128 v214, v[108:111] offset:49184
	ds_write_b128 v215, v[104:107] offset:49184
	ds_write_b128 v214, v[100:103] offset:57376
	ds_write_b128 v215, v[96:99] offset:57376
	s_waitcnt lgkmcnt(0)
	s_barrier
	ds_read_b128 v[152:155], v220 offset:32800
	ds_read_b128 v[156:159], v221 offset:33824
	ds_read_b128 v[160:163], v222 offset:34848
	ds_read_b128 v[164:167], v223 offset:35872
	ds_read_b128 v[168:171], v224 offset:36896
	ds_read_b128 v[172:175], v225 offset:37920
	ds_read_b128 v[176:179], v226 offset:38944
	ds_read_b128 v[236:239], v227 offset:39968
	v_mov_b64_e32 v[232:233], v[230:231]
	s_waitcnt lgkmcnt(7)
	global_store_dwordx4 v[232:233], v[152:155], off sc1
	v_lshl_add_u64 v[232:233], v[232:233], 0, s[96:97]
	s_waitcnt lgkmcnt(6)
	global_store_dwordx4 v[232:233], v[156:159], off sc1
	v_lshl_add_u64 v[232:233], v[232:233], 0, s[96:97]
	s_waitcnt lgkmcnt(5)
	global_store_dwordx4 v[232:233], v[160:163], off sc1
	v_lshl_add_u64 v[232:233], v[232:233], 0, s[96:97]
	s_waitcnt lgkmcnt(4)
	global_store_dwordx4 v[232:233], v[164:167], off sc1
	v_lshl_add_u64 v[232:233], v[232:233], 0, s[96:97]
	s_waitcnt lgkmcnt(3)
	global_store_dwordx4 v[232:233], v[168:171], off sc1
	v_lshl_add_u64 v[232:233], v[232:233], 0, s[96:97]
	s_waitcnt lgkmcnt(2)
	global_store_dwordx4 v[232:233], v[172:175], off sc1
	v_lshl_add_u64 v[232:233], v[232:233], 0, s[96:97]
	s_waitcnt lgkmcnt(1)
	global_store_dwordx4 v[232:233], v[176:179], off sc1
	v_lshl_add_u64 v[232:233], v[232:233], 0, s[96:97]
	s_waitcnt lgkmcnt(0)
	global_store_dwordx4 v[232:233], v[236:239], off sc1
	s_barrier
	ds_write_b128 v214, v[92:95] offset:32800
	ds_write_b128 v215, v[88:91] offset:32800
	ds_write_b128 v214, v[84:87] offset:40992
	ds_write_b128 v215, v[80:83] offset:40992
	ds_write_b128 v214, v[76:79] offset:49184
	ds_write_b128 v215, v[72:75] offset:49184
	ds_write_b128 v214, v[68:71] offset:57376
	ds_write_b128 v215, v[64:67] offset:57376
	s_waitcnt lgkmcnt(0)
	s_barrier
	ds_read_b128 v[152:155], v220 offset:32800
	ds_read_b128 v[156:159], v221 offset:33824
	ds_read_b128 v[160:163], v222 offset:34848
	ds_read_b128 v[164:167], v223 offset:35872
	ds_read_b128 v[168:171], v224 offset:36896
	ds_read_b128 v[172:175], v225 offset:37920
	ds_read_b128 v[176:179], v226 offset:38944
	ds_read_b128 v[236:239], v227 offset:39968
	v_mov_b64_e32 v[232:233], v[230:231]
	s_waitcnt lgkmcnt(7)
	global_store_dwordx4 v[232:233], v[152:155], off offset:512 sc1
	v_lshl_add_u64 v[232:233], v[232:233], 0, s[96:97]
	s_waitcnt lgkmcnt(6)
	global_store_dwordx4 v[232:233], v[156:159], off offset:512 sc1
	v_lshl_add_u64 v[232:233], v[232:233], 0, s[96:97]
	s_waitcnt lgkmcnt(5)
	global_store_dwordx4 v[232:233], v[160:163], off offset:512 sc1
	v_lshl_add_u64 v[232:233], v[232:233], 0, s[96:97]
	s_waitcnt lgkmcnt(4)
	global_store_dwordx4 v[232:233], v[164:167], off offset:512 sc1
	v_lshl_add_u64 v[232:233], v[232:233], 0, s[96:97]
	s_waitcnt lgkmcnt(3)
	global_store_dwordx4 v[232:233], v[168:171], off offset:512 sc1
	v_lshl_add_u64 v[232:233], v[232:233], 0, s[96:97]
	s_waitcnt lgkmcnt(2)
	global_store_dwordx4 v[232:233], v[172:175], off offset:512 sc1
	v_lshl_add_u64 v[232:233], v[232:233], 0, s[96:97]
	s_waitcnt lgkmcnt(1)
	global_store_dwordx4 v[232:233], v[176:179], off offset:512 sc1
	v_lshl_add_u64 v[232:233], v[232:233], 0, s[96:97]
	s_waitcnt lgkmcnt(0)
	global_store_dwordx4 v[232:233], v[236:239], off offset:512 sc1
	s_barrier
	ds_write_b128 v214, v[60:63] offset:32800
	ds_write_b128 v215, v[56:59] offset:32800
	ds_write_b128 v214, v[52:55] offset:40992
	ds_write_b128 v215, v[48:51] offset:40992
	ds_write_b128 v214, v[44:47] offset:49184
	ds_write_b128 v215, v[40:43] offset:49184
	ds_write_b128 v214, v[36:39] offset:57376
	ds_write_b128 v215, v[32:35] offset:57376
	s_waitcnt lgkmcnt(0)
	s_barrier
	ds_read_b128 v[152:155], v220 offset:32800
	ds_read_b128 v[156:159], v221 offset:33824
	ds_read_b128 v[160:163], v222 offset:34848
	ds_read_b128 v[164:167], v223 offset:35872
	ds_read_b128 v[168:171], v224 offset:36896
	ds_read_b128 v[172:175], v225 offset:37920
	ds_read_b128 v[176:179], v226 offset:38944
	ds_read_b128 v[236:239], v227 offset:39968
	v_lshl_add_u64 v[232:233], v[230:231], 0, s[94:95]
	s_waitcnt lgkmcnt(7)
	global_store_dwordx4 v[232:233], v[152:155], off sc1
	v_lshl_add_u64 v[232:233], v[232:233], 0, s[96:97]
	s_waitcnt lgkmcnt(6)
	global_store_dwordx4 v[232:233], v[156:159], off sc1
	v_lshl_add_u64 v[232:233], v[232:233], 0, s[96:97]
	s_waitcnt lgkmcnt(5)
	global_store_dwordx4 v[232:233], v[160:163], off sc1
	v_lshl_add_u64 v[232:233], v[232:233], 0, s[96:97]
	s_waitcnt lgkmcnt(4)
	global_store_dwordx4 v[232:233], v[164:167], off sc1
	v_lshl_add_u64 v[232:233], v[232:233], 0, s[96:97]
	s_waitcnt lgkmcnt(3)
	global_store_dwordx4 v[232:233], v[168:171], off sc1
	v_lshl_add_u64 v[232:233], v[232:233], 0, s[96:97]
	s_waitcnt lgkmcnt(2)
	global_store_dwordx4 v[232:233], v[172:175], off sc1
	v_lshl_add_u64 v[232:233], v[232:233], 0, s[96:97]
	s_waitcnt lgkmcnt(1)
	global_store_dwordx4 v[232:233], v[176:179], off sc1
	v_lshl_add_u64 v[232:233], v[232:233], 0, s[96:97]
	s_waitcnt lgkmcnt(0)
	global_store_dwordx4 v[232:233], v[236:239], off sc1
	s_barrier
	ds_write_b128 v214, v[28:31] offset:32800
	ds_write_b128 v215, v[24:27] offset:32800
	ds_write_b128 v214, v[20:23] offset:40992
	ds_write_b128 v215, v[16:19] offset:40992
	ds_write_b128 v214, v[12:15] offset:49184
	ds_write_b128 v215, v[8:11] offset:49184
	ds_write_b128 v214, v[4:7] offset:57376
	ds_write_b128 v215, v[0:3] offset:57376
	s_waitcnt lgkmcnt(0)
	s_barrier
	ds_read_b128 v[152:155], v220 offset:32800
	ds_read_b128 v[156:159], v221 offset:33824
	ds_read_b128 v[160:163], v222 offset:34848
	ds_read_b128 v[164:167], v223 offset:35872
	ds_read_b128 v[168:171], v224 offset:36896
	ds_read_b128 v[172:175], v225 offset:37920
	ds_read_b128 v[176:179], v226 offset:38944
	ds_read_b128 v[236:239], v227 offset:39968
	v_lshl_add_u64 v[232:233], v[230:231], 0, s[94:95]
	s_waitcnt lgkmcnt(7)
	global_store_dwordx4 v[232:233], v[152:155], off offset:512 sc1
	v_lshl_add_u64 v[232:233], v[232:233], 0, s[96:97]
	s_waitcnt lgkmcnt(6)
	global_store_dwordx4 v[232:233], v[156:159], off offset:512 sc1
	v_lshl_add_u64 v[232:233], v[232:233], 0, s[96:97]
	s_waitcnt lgkmcnt(5)
	global_store_dwordx4 v[232:233], v[160:163], off offset:512 sc1
	v_lshl_add_u64 v[232:233], v[232:233], 0, s[96:97]
	s_waitcnt lgkmcnt(4)
	global_store_dwordx4 v[232:233], v[164:167], off offset:512 sc1
	v_lshl_add_u64 v[232:233], v[232:233], 0, s[96:97]
	s_waitcnt lgkmcnt(3)
	global_store_dwordx4 v[232:233], v[168:171], off offset:512 sc1
	v_lshl_add_u64 v[232:233], v[232:233], 0, s[96:97]
	s_waitcnt lgkmcnt(2)
	global_store_dwordx4 v[232:233], v[172:175], off offset:512 sc1
	v_lshl_add_u64 v[232:233], v[232:233], 0, s[96:97]
	s_waitcnt lgkmcnt(1)
	global_store_dwordx4 v[232:233], v[176:179], off offset:512 sc1
	v_lshl_add_u64 v[232:233], v[232:233], 0, s[96:97]
	s_waitcnt lgkmcnt(0)
	global_store_dwordx4 v[232:233], v[236:239], off offset:512 sc1
	s_barrier
	s_mov_b32 s25, s10
	s_mov_b32 s26, s12
	s_andn2_b64 vcc, exec, s[8:9]
	s_cbranch_vccz .LBB0_1843

.LBB0_2026:
	v_add_u32_e32 v146, s25, v133
	v_min_i32_e32 v144, 0x8000, v146
	v_readlane_b32 s48, v251, 19
	v_ashrrev_i32_e32 v144, 12, v144
	v_readlane_b32 s52, v251, 23
	v_readlane_b32 s53, v251, 24
	v_readlane_b32 s54, v251, 25
	v_readlane_b32 s55, v251, 26
	v_readlane_b32 s56, v251, 27
	v_readlane_b32 s57, v251, 28
	v_readlane_b32 s58, v251, 29
	v_readlane_b32 s59, v251, 30
	v_add_u32_e32 v140, s24, v149
	s_mov_b32 s24, 0x8000
	v_mul_i32_i24_e32 v144, 0x2400, v144
	v_readlane_b32 s60, v251, 31
	v_readlane_b32 s61, v251, 32
	v_readlane_b32 s62, v251, 33
	v_readlane_b32 s63, v251, 34
	s_mov_b64 s[52:53], s[56:57]
	v_readlane_b32 s30, v254, 27
	v_ashrrev_i32_e32 v141, 31, v140
	v_add_u32_e32 v142, 0xffff8000, v146
	v_ashrrev_i32_e32 v143, 31, v146
	v_cmp_gt_i32_e32 vcc, s24, v146
	v_ashrrev_i32_e32 v145, 31, v144
	s_mov_b64 s[54:55], s[58:59]
	v_readlane_b32 s31, v254, 28
	v_cndmask_b32_e32 v143, 0, v143, vcc
	v_cndmask_b32_e32 v142, v142, v146, vcc
	v_mov_b32_e32 v147, s55
	v_mov_b32_e32 v151, s53
	v_mov_b32_e32 v152, s54
	v_mov_b32_e32 v153, s52
	v_lshl_add_u64 v[144:145], v[144:145], 2, s[30:31]
	v_lshlrev_b64 v[140:141], 2, v[140:141]
	v_lshlrev_b64 v[142:143], 12, v[142:143]
	v_cndmask_b32_e32 v155, v147, v151, vcc
	v_cndmask_b32_e32 v154, v152, v153, vcc
	v_lshl_add_u64 v[144:145], v[144:145], 0, v[140:141]
	v_lshl_add_u64 v[142:143], v[154:155], 0, v[142:143]
	v_add_co_u32_e32 v154, vcc, s24, v144
	v_lshl_add_u64 v[142:143], v[142:143], 0, v[140:141]
	s_nop 0
	v_addc_co_u32_e32 v155, vcc, 0, v145, vcc
	s_mov_b64 s[28:29], 0x8000
	v_lshl_add_u64 v[144:145], v[144:145], 0, s[28:29]
	s_movk_i32 s25, 0x7ff0
	v_cmp_gt_i32_e32 vcc, s25, v146
	s_movk_i32 s26, 0x7fe0
	s_movk_i32 s27, 0x7fd0
	v_readlane_b32 s49, v251, 20
	v_readlane_b32 s50, v251, 21
	v_readlane_b32 s51, v251, 22
	s_mov_b64 s[56:57], s[60:61]
	s_mov_b64 s[58:59], s[62:63]
	v_readlane_b32 s48, v251, 3
	v_readlane_b32 s49, v251, 4
	v_readlane_b32 s52, v251, 7
	v_readlane_b32 s53, v251, 8
	v_readlane_b32 s60, v251, 15
	v_readlane_b32 s61, v251, 16
	v_readlane_b32 s50, v251, 5
	v_readlane_b32 s51, v251, 6
	v_readlane_b32 s54, v251, 9
	v_readlane_b32 s55, v251, 10
	v_readlane_b32 s56, v251, 11
	v_readlane_b32 s57, v251, 12
	v_readlane_b32 s58, v251, 13
	v_readlane_b32 s59, v251, 14
	v_readlane_b32 s62, v251, 17
	v_readlane_b32 s63, v251, 18
	s_mov_b64 s[94:95], 0x10000
	s_mov_b64 s[96:97], 0x50000
	global_load_dwordx4 v[152:155], v[144:145], off
	global_load_dwordx4 v[156:159], v[144:145], off offset:64
	global_load_dwordx4 v[160:163], v[144:145], off offset:512
	global_load_dwordx4 v[164:167], v[144:145], off offset:576
	v_mov_b64_e32 v[248:249], v[142:143]
	v_mov_b64_e32 v[140:141], v[142:143]
	global_load_dwordx4 v[168:171], v[248:249], off
	global_load_dwordx4 v[172:175], v[248:249], off offset:64
	global_load_dwordx4 v[176:179], v[248:249], off offset:512
	global_load_dwordx4 v[204:207], v[248:249], off offset:576
	v_lshl_add_u64 v[248:249], v[248:249], 0, s[94:95]
	global_load_dwordx4 v[208:211], v[248:249], off
	global_load_dwordx4 v[212:215], v[248:249], off offset:64
	global_load_dwordx4 v[216:219], v[248:249], off offset:512
	global_load_dwordx4 v[220:223], v[248:249], off offset:576
	v_lshl_add_u64 v[248:249], v[248:249], 0, s[94:95]
	global_load_dwordx4 v[224:227], v[248:249], off
	global_load_dwordx4 v[228:231], v[248:249], off offset:64
	global_load_dwordx4 v[232:235], v[248:249], off offset:512
	global_load_dwordx4 v[236:239], v[248:249], off offset:576
	v_lshl_add_u64 v[248:249], v[248:249], 0, s[94:95]
	global_load_dwordx4 v[240:243], v[248:249], off
	global_load_dwordx4 v[244:247], v[248:249], off offset:64
	s_waitcnt vmcnt(13)
	v_pk_mul_f32 v[154:155], v[154:155], 0.5 op_sel_hi:[1,0]
	v_pk_mul_f32 v[152:153], v[152:153], 0.5 op_sel_hi:[1,0]
	v_pk_mul_f32 v[158:159], v[158:159], 0.5 op_sel_hi:[1,0]
	v_pk_mul_f32 v[156:157], v[156:157], 0.5 op_sel_hi:[1,0]
	v_pk_mul_f32 v[162:163], v[162:163], 0.5 op_sel_hi:[1,0]
	v_pk_mul_f32 v[160:161], v[160:161], 0.5 op_sel_hi:[1,0]
	v_pk_mul_f32 v[166:167], v[166:167], 0.5 op_sel_hi:[1,0]
	v_pk_mul_f32 v[164:165], v[164:165], 0.5 op_sel_hi:[1,0]
	v_pk_fma_f32 v[126:127], v[126:127], v[154:155], v[170:171]
	v_pk_fma_f32 v[124:125], v[124:125], v[152:153], v[168:169]
	global_load_dwordx4 v[168:171], v[248:249], off offset:512
	s_waitcnt vmcnt(13)
	v_pk_fma_f32 v[122:123], v[122:123], v[158:159], v[174:175]
	v_pk_fma_f32 v[120:121], v[120:121], v[156:157], v[172:173]
	global_load_dwordx4 v[172:175], v[248:249], off offset:576
	s_waitcnt vmcnt(13)
	v_pk_fma_f32 v[98:99], v[98:99], v[162:163], v[178:179]
	v_pk_fma_f32 v[96:97], v[96:97], v[160:161], v[176:177]
	v_lshl_add_u64 v[248:249], v[248:249], 0, s[96:97]
	global_load_dwordx4 v[176:179], v[248:249], off
	s_waitcnt vmcnt(13)
	v_pk_fma_f32 v[90:91], v[90:91], v[166:167], v[206:207]
	v_pk_fma_f32 v[88:89], v[88:89], v[164:165], v[204:205]
	global_load_dwordx4 v[204:207], v[248:249], off offset:64
	s_waitcnt vmcnt(13)
	v_pk_fma_f32 v[118:119], v[118:119], v[154:155], v[210:211]
	v_pk_fma_f32 v[116:117], v[116:117], v[152:153], v[208:209]
	global_load_dwordx4 v[208:211], v[248:249], off offset:512
	s_waitcnt vmcnt(13)
	v_pk_fma_f32 v[114:115], v[114:115], v[158:159], v[214:215]
	v_pk_fma_f32 v[112:113], v[112:113], v[156:157], v[212:213]
	global_load_dwordx4 v[212:215], v[248:249], off offset:576
	s_waitcnt vmcnt(13)
	v_pk_fma_f32 v[86:87], v[86:87], v[162:163], v[218:219]
	v_pk_fma_f32 v[84:85], v[84:85], v[160:161], v[216:217]
	v_lshl_add_u64 v[248:249], v[248:249], 0, s[94:95]
	global_load_dwordx4 v[216:219], v[248:249], off
	s_waitcnt vmcnt(13)
	v_pk_fma_f32 v[82:83], v[82:83], v[166:167], v[222:223]
	v_pk_fma_f32 v[80:81], v[80:81], v[164:165], v[220:221]
	global_load_dwordx4 v[220:223], v[248:249], off offset:64
	s_waitcnt vmcnt(13)
	v_pk_fma_f32 v[110:111], v[110:111], v[154:155], v[226:227]
	v_pk_fma_f32 v[108:109], v[108:109], v[152:153], v[224:225]
	global_load_dwordx4 v[224:227], v[248:249], off offset:512
	s_waitcnt vmcnt(13)
	v_pk_fma_f32 v[106:107], v[106:107], v[158:159], v[230:231]
	v_pk_fma_f32 v[104:105], v[104:105], v[156:157], v[228:229]
	global_load_dwordx4 v[228:231], v[248:249], off offset:576
	s_waitcnt vmcnt(13)
	v_pk_fma_f32 v[78:79], v[78:79], v[162:163], v[234:235]
	v_pk_fma_f32 v[76:77], v[76:77], v[160:161], v[232:233]
	v_lshl_add_u64 v[248:249], v[248:249], 0, s[94:95]
	global_load_dwordx4 v[232:235], v[248:249], off
	s_waitcnt vmcnt(13)
	v_pk_fma_f32 v[74:75], v[74:75], v[166:167], v[238:239]
	v_pk_fma_f32 v[72:73], v[72:73], v[164:165], v[236:237]
	global_load_dwordx4 v[236:239], v[248:249], off offset:64
	s_waitcnt vmcnt(13)
	v_pk_fma_f32 v[102:103], v[102:103], v[154:155], v[242:243]
	v_pk_fma_f32 v[100:101], v[100:101], v[152:153], v[240:241]
	global_load_dwordx4 v[240:243], v[248:249], off offset:512
	s_waitcnt vmcnt(13)
	v_pk_fma_f32 v[94:95], v[94:95], v[158:159], v[246:247]
	v_pk_fma_f32 v[92:93], v[92:93], v[156:157], v[244:245]
	global_load_dwordx4 v[244:247], v[248:249], off offset:576
	s_waitcnt vmcnt(13)
	v_pk_fma_f32 v[70:71], v[70:71], v[162:163], v[170:171]
	v_pk_fma_f32 v[68:69], v[68:69], v[160:161], v[168:169]
	v_lshl_add_u64 v[248:249], v[248:249], 0, s[94:95]
	global_load_dwordx4 v[168:171], v[248:249], off
	s_waitcnt vmcnt(13)
	v_pk_fma_f32 v[62:63], v[62:63], v[166:167], v[174:175]
	v_pk_fma_f32 v[60:61], v[60:61], v[164:165], v[172:173]
	global_load_dwordx4 v[172:175], v[248:249], off offset:64
	s_waitcnt vmcnt(13)
	v_pk_fma_f32 v[66:67], v[66:67], v[154:155], v[178:179]
	v_pk_fma_f32 v[64:65], v[64:65], v[152:153], v[176:177]
	global_load_dwordx4 v[176:179], v[248:249], off offset:512
	s_waitcnt vmcnt(13)
	v_pk_fma_f32 v[58:59], v[58:59], v[158:159], v[206:207]
	v_pk_fma_f32 v[56:57], v[56:57], v[156:157], v[204:205]
	global_load_dwordx4 v[204:207], v[248:249], off offset:576
	s_waitcnt vmcnt(13)
	v_pk_fma_f32 v[30:31], v[30:31], v[162:163], v[210:211]
	v_pk_fma_f32 v[28:29], v[28:29], v[160:161], v[208:209]
	s_waitcnt vmcnt(12)
	v_pk_fma_f32 v[26:27], v[26:27], v[166:167], v[214:215]
	v_pk_fma_f32 v[24:25], v[24:25], v[164:165], v[212:213]
	s_waitcnt vmcnt(11)
	v_pk_fma_f32 v[54:55], v[54:55], v[154:155], v[218:219]
	v_pk_fma_f32 v[52:53], v[52:53], v[152:153], v[216:217]
	s_waitcnt vmcnt(10)
	v_pk_fma_f32 v[50:51], v[50:51], v[158:159], v[222:223]
	v_pk_fma_f32 v[48:49], v[48:49], v[156:157], v[220:221]
	s_waitcnt vmcnt(9)
	v_pk_fma_f32 v[22:23], v[22:23], v[162:163], v[226:227]
	v_pk_fma_f32 v[20:21], v[20:21], v[160:161], v[224:225]
	s_waitcnt vmcnt(8)
	v_pk_fma_f32 v[18:19], v[18:19], v[166:167], v[230:231]
	v_pk_fma_f32 v[16:17], v[16:17], v[164:165], v[228:229]
	s_waitcnt vmcnt(7)
	v_pk_fma_f32 v[46:47], v[46:47], v[154:155], v[234:235]
	v_pk_fma_f32 v[44:45], v[44:45], v[152:153], v[232:233]
	s_waitcnt vmcnt(6)
	v_pk_fma_f32 v[42:43], v[42:43], v[158:159], v[238:239]
	v_pk_fma_f32 v[40:41], v[40:41], v[156:157], v[236:237]
	s_waitcnt vmcnt(5)
	v_pk_fma_f32 v[14:15], v[14:15], v[162:163], v[242:243]
	v_pk_fma_f32 v[12:13], v[12:13], v[160:161], v[240:241]
	s_waitcnt vmcnt(4)
	v_pk_fma_f32 v[10:11], v[10:11], v[166:167], v[246:247]
	v_pk_fma_f32 v[8:9], v[8:9], v[164:165], v[244:245]
	s_waitcnt vmcnt(3)
	v_pk_fma_f32 v[38:39], v[38:39], v[154:155], v[170:171]
	v_pk_fma_f32 v[36:37], v[36:37], v[152:153], v[168:169]
	s_waitcnt vmcnt(2)
	v_pk_fma_f32 v[34:35], v[34:35], v[158:159], v[174:175]
	v_pk_fma_f32 v[32:33], v[32:33], v[156:157], v[172:173]
	s_waitcnt vmcnt(1)
	v_pk_fma_f32 v[6:7], v[6:7], v[162:163], v[178:179]
	v_pk_fma_f32 v[4:5], v[4:5], v[160:161], v[176:177]
	s_waitcnt vmcnt(0)
	v_pk_fma_f32 v[2:3], v[2:3], v[166:167], v[206:207]
	v_pk_fma_f32 v[0:1], v[0:1], v[164:165], v[204:205]
	v_and_b32_e32 v204, 63, v131
	v_lshrrev_b32_e32 v205, 6, v131
	v_and_b32_e32 v206, 15, v204
	v_lshrrev_b32_e32 v207, 4, v204
	v_lshrrev_b32_e32 v208, 2, v205
	v_and_b32_e32 v209, 3, v205
	v_lshl_add_u32 v210, v208, 6, v206
	v_lshlrev_b32_e32 v210, 12, v210
	v_lshl_add_u32 v210, v209, 7, v210
	v_lshl_add_u32 v210, v207, 4, v210
	v_sub_co_u32_e32 v212, vcc, v140, v210
	s_nop 0
	v_subbrev_co_u32_e32 v213, vcc, 0, v141, vcc
	v_lshl_add_u32 v214, v209, 3, v207
	v_xor_b32_e32 v214, v214, v206
	v_lshlrev_b32_e32 v214, 4, v214
	v_lshl_add_u32 v214, v206, 9, v214
	v_lshl_add_u32 v214, v208, 16, v214
	v_xor_b32_e32 v215, 64, v214
	v_lshrrev_b32_e32 v216, 5, v204
	v_and_b32_e32 v217, 31, v204
	v_and_b32_e32 v218, 3, v205
	v_lshl_add_u32 v218, v218, 4, v216
	v_lshlrev_b32_e32 v218, 9, v218
	v_lshrrev_b32_e32 v219, 2, v205
	v_lshl_add_u32 v218, v219, 16, v218
	v_xor_b32_e32 v219, v217, v216
	v_lshl_add_u32 v218, v219, 4, v218
	v_mov_b32_e32 v220, v218
	v_xor_b32_e32 v221, 32, v218
	v_xor_b32_e32 v222, 64, v218
	v_xor_b32_e32 v223, 0x60, v218
	v_xor_b32_e32 v224, 0x80, v218
	v_xor_b32_e32 v225, 0xa0, v218
	v_xor_b32_e32 v226, 0xc0, v218
	v_xor_b32_e32 v227, 0xe0, v218
	v_lshl_add_u32 v228, v205, 4, v216
	v_lshlrev_b32_e32 v228, 12, v228
	v_lshl_add_u32 v228, v217, 4, v228
	v_mov_b32_e32 v229, 0
	v_lshl_add_u64 v[230:231], v[212:213], 0, v[228:229]
	s_mov_b64 s[94:95], 0x80000
	s_mov_b64 s[96:97], 0x2000
	ds_write_b128 v214, v[124:127] offset:32800
	ds_write_b128 v215, v[120:123] offset:32800
	ds_write_b128 v214, v[116:119] offset:40992
	ds_write_b128 v215, v[112:115] offset:40992
	ds_write_b128 v214, v[108:111] offset:49184
	ds_write_b128 v215, v[104:107] offset:49184
	ds_write_b128 v214, v[100:103] offset:57376
	ds_write_b128 v215, v[92:95] offset:57376
	s_waitcnt lgkmcnt(0)
	s_barrier
	ds_read_b128 v[152:155], v220 offset:32800
	ds_read_b128 v[156:159], v221 offset:33824
	ds_read_b128 v[160:163], v222 offset:34848
	ds_read_b128 v[164:167], v223 offset:35872
	ds_read_b128 v[168:171], v224 offset:36896
	ds_read_b128 v[172:175], v225 offset:37920
	ds_read_b128 v[176:179], v226 offset:38944
	ds_read_b128 v[236:239], v227 offset:39968
	v_mov_b64_e32 v[232:233], v[230:231]
	s_waitcnt lgkmcnt(7)
	global_store_dwordx4 v[232:233], v[152:155], off sc1
	v_lshl_add_u64 v[232:233], v[232:233], 0, s[96:97]
	s_waitcnt lgkmcnt(6)
	global_store_dwordx4 v[232:233], v[156:159], off sc1
	v_lshl_add_u64 v[232:233], v[232:233], 0, s[96:97]
	s_waitcnt lgkmcnt(5)
	global_store_dwordx4 v[232:233], v[160:163], off sc1
	v_lshl_add_u64 v[232:233], v[232:233], 0, s[96:97]
	s_waitcnt lgkmcnt(4)
	global_store_dwordx4 v[232:233], v[164:167], off sc1
	v_lshl_add_u64 v[232:233], v[232:233], 0, s[96:97]
	s_waitcnt lgkmcnt(3)
	global_store_dwordx4 v[232:233], v[168:171], off sc1
	v_lshl_add_u64 v[232:233], v[232:233], 0, s[96:97]
	s_waitcnt lgkmcnt(2)
	global_store_dwordx4 v[232:233], v[172:175], off sc1
	v_lshl_add_u64 v[232:233], v[232:233], 0, s[96:97]
	s_waitcnt lgkmcnt(1)
	global_store_dwordx4 v[232:233], v[176:179], off sc1
	v_lshl_add_u64 v[232:233], v[232:233], 0, s[96:97]
	s_waitcnt lgkmcnt(0)
	global_store_dwordx4 v[232:233], v[236:239], off sc1
	s_barrier
	ds_write_b128 v214, v[96:99] offset:32800
	ds_write_b128 v215, v[88:91] offset:32800
	ds_write_b128 v214, v[84:87] offset:40992
	ds_write_b128 v215, v[80:83] offset:40992
	ds_write_b128 v214, v[76:79] offset:49184
	ds_write_b128 v215, v[72:75] offset:49184
	ds_write_b128 v214, v[68:71] offset:57376
	ds_write_b128 v215, v[60:63] offset:57376
	s_waitcnt lgkmcnt(0)
	s_barrier
	ds_read_b128 v[152:155], v220 offset:32800
	ds_read_b128 v[156:159], v221 offset:33824
	ds_read_b128 v[160:163], v222 offset:34848
	ds_read_b128 v[164:167], v223 offset:35872
	ds_read_b128 v[168:171], v224 offset:36896
	ds_read_b128 v[172:175], v225 offset:37920
	ds_read_b128 v[176:179], v226 offset:38944
	ds_read_b128 v[236:239], v227 offset:39968
	v_mov_b64_e32 v[232:233], v[230:231]
	s_waitcnt lgkmcnt(7)
	global_store_dwordx4 v[232:233], v[152:155], off offset:512 sc1
	v_lshl_add_u64 v[232:233], v[232:233], 0, s[96:97]
	s_waitcnt lgkmcnt(6)
	global_store_dwordx4 v[232:233], v[156:159], off offset:512 sc1
	v_lshl_add_u64 v[232:233], v[232:233], 0, s[96:97]
	s_waitcnt lgkmcnt(5)
	global_store_dwordx4 v[232:233], v[160:163], off offset:512 sc1
	v_lshl_add_u64 v[232:233], v[232:233], 0, s[96:97]
	s_waitcnt lgkmcnt(4)
	global_store_dwordx4 v[232:233], v[164:167], off offset:512 sc1
	v_lshl_add_u64 v[232:233], v[232:233], 0, s[96:97]
	s_waitcnt lgkmcnt(3)
	global_store_dwordx4 v[232:233], v[168:171], off offset:512 sc1
	v_lshl_add_u64 v[232:233], v[232:233], 0, s[96:97]
	s_waitcnt lgkmcnt(2)
	global_store_dwordx4 v[232:233], v[172:175], off offset:512 sc1
	v_lshl_add_u64 v[232:233], v[232:233], 0, s[96:97]
	s_waitcnt lgkmcnt(1)
	global_store_dwordx4 v[232:233], v[176:179], off offset:512 sc1
	v_lshl_add_u64 v[232:233], v[232:233], 0, s[96:97]
	s_waitcnt lgkmcnt(0)
	global_store_dwordx4 v[232:233], v[236:239], off offset:512 sc1
	s_barrier
	ds_write_b128 v214, v[64:67] offset:32800
	ds_write_b128 v215, v[56:59] offset:32800
	ds_write_b128 v214, v[52:55] offset:40992
	ds_write_b128 v215, v[48:51] offset:40992
	ds_write_b128 v214, v[44:47] offset:49184
	ds_write_b128 v215, v[40:43] offset:49184
	ds_write_b128 v214, v[36:39] offset:57376
	ds_write_b128 v215, v[32:35] offset:57376
	s_waitcnt lgkmcnt(0)
	s_barrier
	ds_read_b128 v[152:155], v220 offset:32800
	ds_read_b128 v[156:159], v221 offset:33824
	ds_read_b128 v[160:163], v222 offset:34848
	ds_read_b128 v[164:167], v223 offset:35872
	ds_read_b128 v[168:171], v224 offset:36896
	ds_read_b128 v[172:175], v225 offset:37920
	ds_read_b128 v[176:179], v226 offset:38944
	ds_read_b128 v[236:239], v227 offset:39968
	v_lshl_add_u64 v[232:233], v[230:231], 0, s[94:95]
	s_waitcnt lgkmcnt(7)
	global_store_dwordx4 v[232:233], v[152:155], off sc1
	v_lshl_add_u64 v[232:233], v[232:233], 0, s[96:97]
	s_waitcnt lgkmcnt(6)
	global_store_dwordx4 v[232:233], v[156:159], off sc1
	v_lshl_add_u64 v[232:233], v[232:233], 0, s[96:97]
	s_waitcnt lgkmcnt(5)
	global_store_dwordx4 v[232:233], v[160:163], off sc1
	v_lshl_add_u64 v[232:233], v[232:233], 0, s[96:97]
	s_waitcnt lgkmcnt(4)
	global_store_dwordx4 v[232:233], v[164:167], off sc1
	v_lshl_add_u64 v[232:233], v[232:233], 0, s[96:97]
	s_waitcnt lgkmcnt(3)
	global_store_dwordx4 v[232:233], v[168:171], off sc1
	v_lshl_add_u64 v[232:233], v[232:233], 0, s[96:97]
	s_waitcnt lgkmcnt(2)
	global_store_dwordx4 v[232:233], v[172:175], off sc1
	v_lshl_add_u64 v[232:233], v[232:233], 0, s[96:97]
	s_waitcnt lgkmcnt(1)
	global_store_dwordx4 v[232:233], v[176:179], off sc1
	v_lshl_add_u64 v[232:233], v[232:233], 0, s[96:97]
	s_waitcnt lgkmcnt(0)
	global_store_dwordx4 v[232:233], v[236:239], off sc1
	s_barrier
	ds_write_b128 v214, v[28:31] offset:32800
	ds_write_b128 v215, v[24:27] offset:32800
	ds_write_b128 v214, v[20:23] offset:40992
	ds_write_b128 v215, v[16:19] offset:40992
	ds_write_b128 v214, v[12:15] offset:49184
	ds_write_b128 v215, v[8:11] offset:49184
	ds_write_b128 v214, v[4:7] offset:57376
	ds_write_b128 v215, v[0:3] offset:57376
	s_waitcnt lgkmcnt(0)
	s_barrier
	ds_read_b128 v[152:155], v220 offset:32800
	ds_read_b128 v[156:159], v221 offset:33824
	ds_read_b128 v[160:163], v222 offset:34848
	ds_read_b128 v[164:167], v223 offset:35872
	ds_read_b128 v[168:171], v224 offset:36896
	ds_read_b128 v[172:175], v225 offset:37920
	ds_read_b128 v[176:179], v226 offset:38944
	ds_read_b128 v[236:239], v227 offset:39968
	v_lshl_add_u64 v[232:233], v[230:231], 0, s[94:95]
	s_waitcnt lgkmcnt(7)
	global_store_dwordx4 v[232:233], v[152:155], off offset:512 sc1
	v_lshl_add_u64 v[232:233], v[232:233], 0, s[96:97]
	s_waitcnt lgkmcnt(6)
	global_store_dwordx4 v[232:233], v[156:159], off offset:512 sc1
	v_lshl_add_u64 v[232:233], v[232:233], 0, s[96:97]
	s_waitcnt lgkmcnt(5)
	global_store_dwordx4 v[232:233], v[160:163], off offset:512 sc1
	v_lshl_add_u64 v[232:233], v[232:233], 0, s[96:97]
	s_waitcnt lgkmcnt(4)
	global_store_dwordx4 v[232:233], v[164:167], off offset:512 sc1
	v_lshl_add_u64 v[232:233], v[232:233], 0, s[96:97]
	s_waitcnt lgkmcnt(3)
	global_store_dwordx4 v[232:233], v[168:171], off offset:512 sc1
	v_lshl_add_u64 v[232:233], v[232:233], 0, s[96:97]
	s_waitcnt lgkmcnt(2)
	global_store_dwordx4 v[232:233], v[172:175], off offset:512 sc1
	v_lshl_add_u64 v[232:233], v[232:233], 0, s[96:97]
	s_waitcnt lgkmcnt(1)
	global_store_dwordx4 v[232:233], v[176:179], off offset:512 sc1
	v_lshl_add_u64 v[232:233], v[232:233], 0, s[96:97]
	s_waitcnt lgkmcnt(0)
	global_store_dwordx4 v[232:233], v[236:239], off offset:512 sc1
	s_barrier
	s_mov_b32 s25, s23
	s_mov_b32 s24, s22
	s_andn2_b64 vcc, exec, s[10:11]
	s_cbranch_vccz .LBB0_2038
